# v015 + P5 staging remap: each wave now fetches both 64-byte halves of its 16 rows (LDS block 2w+i instead of w+8i) so paired half-line requests come from one wave
# baseline (speedup 1.0000x reference)
; #define PG8_STAGE(bufoff, gbase, voff) do { _Pragma("unroll") for (int _i = 0; _i < 2; ++_i) \
;         __builtin_amdgcn_global_load_lds((const unsigned*)((const char*)(gbase) + (voff)[_i]), (LAS unsigned*)(lds + (bufoff) + ldsw + _i * 8192), 16, 0, 0); } while (0)
; #define PG8_WAIT_V(n) asm volatile("s_waitcnt vmcnt(" #n ")" ::: "memory")
; #define PG8_BAR __builtin_amdgcn_s_barrier()
; template <class Epi, class Sched, bool ALIGN_EPI, bool SP2>
; __device__ __forceinline__ void gemm_phase(LAS unsigned char* lds, const Gemm g, const Sched& S, const Epi& E) {
;     ...
;     for (int i = 0; i < 2; ++i) { int R, C; stage_rc(tid * 16 + i * 8192, R, C); const int Rb = Epi::PERM ? ((R & ~31) + perm32(R & 31)) : R;
;         voffA[i] = (unsigned)(R * K + C) * 2u; voffB[i] = (unsigned)((Epi::BMODE ? 64 * Rb : Rb) * K + C) * 2u; }
;     const size_t kstep = (size_t)(BK * 2);
;     const size_t hstep = (size_t)HALF * K * 2;
;     const size_t tstep = 2 * hstep;
;     const size_t hstepB = Epi::BMODE ? (size_t)K * 2 : hstep;
;     ...
;     const unsigned ldsw = (unsigned)wid * 1024u;
;     const int aoff = lds_byte(wr * 64 + fr, fq * 8), boff = lds_byte(wc * 32 + fr, fq * 8);
;     ...
;     if constexpr (SP2) {
;         PG8_STAGE(PG8_SB(0, 0), cB, voffB); PG8_STAGE(PG8_SB(0, 1), cB + hstepB, voffB); PG8_STAGE(PG8_SA(0, 0), cA, voffA); PG8_STAGE(PG8_SA(0, 1), cA + hstep, voffA);
;         if (wr == 1) PG8_BAR;
;         PG8_WAIT_V(2); PG8_BAR;
;         PG8_STAGE(PG8_SB(1, 0), cB + kstep, voffB); PG8_STAGE(PG8_SA(1, 0), cA + kstep, voffA); PG8_STAGE(PG8_SB(1, 1), cB + hstepB + kstep, voffB);
;         PG8_WAIT_V(6); PG8_BAR;
.LBB0_970:
	v_ashrrev_i32_e32 v1, 31, v8
	v_lshrrev_b32_e32 v1, 26, v1
	v_add_u32_e32 v1, v8, v1
	v_ashrrev_i32_e32 v9, 6, v1
	v_lshlrev_b32_e32 v9, 1, v9
	v_bfe_i32 v1, v8, 27, 1
	v_lshlrev_b32_e32 v0, 4, v8
	v_lshrrev_b32_e32 v1, 22, v1
	v_add_u32_e32 v1, v0, v1
	v_and_b32_e32 v1, 0xfffffc00, v1
	v_sub_u32_e32 v1, v0, v1
	v_lshrrev_b32_e32 v2, 4, v1
	v_bitop3_b32 v1, v2, v1, 32 bitop3:0x6c
	s_ashr_i32 s71, s70, 31
	v_ashrrev_i32_e32 v3, 31, v1
	s_lshl_b64 s[0:1], s[70:71], 20
	v_lshrrev_b32_e32 v3, 26, v3
	s_add_u32 s76, s26, s0
	v_add_u32_e32 v3, v1, v3
	s_addc_u32 s77, s27, s1
	s_ashr_i32 s73, s72, 31
	v_lshlrev_b32_e32 v2, 3, v9
	v_ashrrev_i32_e32 v10, 6, v3
	v_and_b32_e32 v3, 0xc0, v3
	s_lshl_b64 s[0:1], s[72:73], 20
	v_and_b32_e32 v2, -16, v2
	v_sub_u32_e32 v1, v1, v3
	v_mov_b32_e32 v3, 1
	s_add_u32 s78, s60, s0
	v_add_u32_e32 v2, v10, v2
	v_ashrrev_i16_sdwa v1, v3, sext(v1) dst_sel:DWORD dst_unused:UNUSED_PAD src0_sel:DWORD src1_sel:BYTE_0
	s_addc_u32 s79, s61, s1
	v_lshlrev_b32_e32 v4, 5, v9
	v_bfe_i32 v11, v1, 0, 16
	v_lshlrev_b32_e32 v1, 1, v2
	v_lshrrev_b32_e32 v5, 2, v2
	v_and_b32_e32 v6, 3, v10
	s_mov_b32 s1, 0xfffe0
	v_and_b32_e32 v4, 32, v4
	v_and_b32_e32 v1, 24, v1
	v_and_b32_e32 v5, 4, v5
	v_and_or_b32 v6, v2, s1, v6
	v_or3_b32 v1, v6, v5, v1
	v_add_lshl_u32 v4, v4, v11, 1
	v_add_u32_e32 v0, 0x2000, v0
	v_lshl_add_u32 v134, v1, 12, v4
	v_ashrrev_i32_e32 v1, 31, v0
	v_lshrrev_b32_e32 v1, 22, v1
	v_add_u32_e32 v1, v0, v1
	v_ashrrev_i32_e32 v12, 10, v1
	v_mul_i32_i24_e32 v1, 0x400, v12
	v_lshl_add_u32 v12, v12, 1, -15
	v_sub_u32_e32 v0, v0, v1
	v_lshrrev_b32_e32 v1, 4, v0
	v_bitop3_b32 v0, v1, v0, 32 bitop3:0x6c
	v_lshl_add_u32 v132, v2, 12, v4
	v_ashrrev_i32_e32 v2, 31, v0
	v_lshrrev_b32_e32 v2, 26, v2
	v_add_u32_e32 v2, v0, v2
	v_lshlrev_b32_e32 v1, 3, v12
	v_ashrrev_i32_e32 v13, 6, v2
	v_and_b32_e32 v2, 0xc0, v2
	v_and_b32_e32 v1, -16, v1
	v_sub_u32_e32 v0, v0, v2
	s_ashr_i32 s4, s6, 6
	v_add_u32_e32 v1, v13, v1
	v_ashrrev_i16_sdwa v0, v3, sext(v0) dst_sel:DWORD dst_unused:UNUSED_PAD src0_sel:DWORD src1_sel:BYTE_0
	s_lshl_b32 s57, s4, 11
	v_lshlrev_b32_e32 v4, 5, v12
	v_bfe_i32 v14, v0, 0, 16
	v_lshlrev_b32_e32 v0, 1, v1
	v_lshrrev_b32_e32 v2, 2, v1
	v_and_b32_e32 v3, 3, v13
	s_add_i32 s59, s57, 0
	v_and_b32_e32 v4, 32, v4
	v_and_b32_e32 v0, 24, v0
	v_and_b32_e32 v2, 4, v2
	v_and_or_b32 v3, v1, s1, v3
	s_add_i32 m0, s59, 0x10000
	s_ashr_i32 s0, s6, 8
	v_or3_b32 v0, v3, v2, v0
	v_add_lshl_u32 v2, v4, v14, 1
	global_load_lds_dwordx4 v134, s[78:79]
	s_add_i32 m0, s59, 0x10400
	v_lshl_add_u32 v138, v0, 12, v2
	s_add_u32 s8, s78, 0x80000
	global_load_lds_dwordx4 v138, s[78:79]
	s_addc_u32 s9, s79, 0
	s_add_i32 m0, s59, 0x14000
	s_add_i32 s73, s59, 0x400
	global_load_lds_dwordx4 v134, s[8:9]
	s_add_i32 m0, s59, 0x14400
	v_lshl_add_u32 v136, v1, 12, v2
	global_load_lds_dwordx4 v138, s[8:9]
	s_mov_b32 m0, s59
	s_add_u32 s8, s76, 0x80000
	global_load_lds_dwordx4 v132, s[76:77]
	s_mov_b32 m0, s73
	s_addc_u32 s9, s77, 0
	s_add_i32 s84, s59, 0x4000
	global_load_lds_dwordx4 v136, s[76:77]
	s_mov_b32 m0, s84
	s_add_i32 s85, s59, 0x4400
	global_load_lds_dwordx4 v132, s[8:9]
	s_mov_b32 m0, s85
	v_mov_b32_e32 v141, 0
	global_load_lds_dwordx4 v136, s[8:9]
	v_mov_b32_e32 v135, v141
	v_mov_b32_e32 v139, v141
	v_mov_b32_e32 v133, v141
	v_mov_b32_e32 v137, v141
	s_cmp_eq_u32 s0, 1
	s_mov_b32 s2, s91
	v_writelane_b32 v242, s92, 6
	s_mov_b32 s1, 0
	v_lshl_add_u64 v[6:7], s[78:79], 0, v[134:135]
	v_lshl_add_u64 v[4:5], s[78:79], 0, v[138:139]
	v_lshl_add_u64 v[0:1], s[76:77], 0, v[132:133]
	s_cselect_b64 s[40:41], -1, 0
	s_cmp_lg_u32 s0, 1
	v_lshl_add_u64 v[2:3], s[76:77], 0, v[136:137]
	v_writelane_b32 v242, s93, 7
	s_cbranch_scc1 .LBB0_972
	s_barrier
.LBB0_972:
	s_lshl_b32 s4, s4, 5
	s_mov_b64 s[42:43], 0x80
	s_and_b32 s7, s4, 0x60
	s_add_i32 m0, s59, 0x18000
	v_lshl_add_u64 v[6:7], v[6:7], 0, s[42:43]
	s_lshl_b32 s86, s0, 6
	s_lshl_b32 s0, s0, 13
	s_lshl_b32 s8, s7, 7
	s_waitcnt vmcnt(2)
	s_barrier
	global_load_lds_dwordx4 v[6:7], off
	v_lshl_add_u64 v[4:5], v[4:5], 0, s[42:43]
	s_add_i32 m0, s59, 0x18400
	s_add_i32 s87, s59, 0x8000
	s_add_i32 s88, s59, 0x8400
	global_load_lds_dwordx4 v[4:5], off
	v_lshl_add_u64 v[0:1], v[0:1], 0, s[42:43]
	s_mov_b32 m0, s87
	s_add_u32 s4, s78, 0x80080
	global_load_lds_dwordx4 v[0:1], off
	v_lshl_add_u64 v[0:1], v[2:3], 0, s[42:43]
	s_mov_b32 m0, s88
	s_addc_u32 s5, s79, 0
	global_load_lds_dwordx4 v[0:1], off
	s_add_i32 m0, s59, 0x1c000
	v_lshl_add_u64 v[0:1], s[4:5], 0, v[134:135]
	global_load_lds_dwordx4 v[0:1], off
	v_lshl_add_u64 v[0:1], s[4:5], 0, v[138:139]
	s_add_i32 m0, s59, 0x1c400
	v_and_b32_e32 v209, 15, v8
	global_load_lds_dwordx4 v[0:1], off
	v_lshrrev_b32_e32 v0, 1, v8
	v_and_b32_e32 v0, 24, v0
	v_lshlrev_b32_e32 v1, 1, v0
	v_lshlrev_b32_e32 v2, 2, v8
	v_or_b32_e32 v211, s7, v0
	v_lshlrev_b32_e32 v0, 15, v9
	v_lshl_or_b32 v1, v209, 6, v1
	v_and_b32_e32 v2, 32, v2
	v_and_b32_e32 v0, 0xffff0000, v0
	v_bitop3_b32 v3, v1, s0, v2 bitop3:0xde
	v_bitop3_b32 v210, v1, s8, v2 bitop3:0xde
	v_lshl_add_u32 v0, v10, 12, v0
	v_and_b32_e32 v1, 1, v9
	v_lshl_or_b32 v0, v1, 6, v0
	v_lshl_add_u32 v142, v11, 1, v0
	v_lshlrev_b32_e32 v0, 15, v12
	v_and_b32_e32 v0, 0xffff0000, v0
	s_waitcnt vmcnt(6)
	v_lshl_add_u32 v0, v13, 12, v0
	v_and_b32_e32 v1, 1, v12
	s_cmpk_lt_u32 s6, 0x100
	v_lshl_or_b32 v0, v1, 6, v0
	s_cselect_b64 s[44:45], -1, 0
	v_lshlrev_b32_e32 v212, 2, v211
	v_cmp_gt_u32_e64 s[4:5], 2, v209
	v_cmp_lt_u32_e64 s[6:7], 13, v209
	v_add_u32_e32 v213, -12, v209
	v_cmp_ne_u32_e64 s[8:9], 15, v209
	v_cmp_ne_u32_e64 s[10:11], 0, v209
	v_mov_b32_e32 v143, v141
	v_lshl_add_u32 v144, v14, 1, v0
	v_mov_b32_e32 v145, v141
	s_mov_b64 s[46:47], -1
	s_mov_b64 s[50:51], 0
	v_mov_b64_e32 v[146:147], 0x2100
	v_mov_b64_e32 v[148:149], 0x20ff
	s_add_i32 s89, 0, 0x10000
	s_add_i32 s90, 0, 0x14000
	v_add_u32_e32 v214, 0, v3
	v_mov_b32_e32 v215, 0x358637bd
	s_movk_i32 s91, 0x5800
	s_mov_b32 s92, 0x2c000
	s_mov_b32 s93, 0x58000
	s_mov_b32 s94, 0x18c000
	s_mov_b32 s95, 0x1b8000
	s_mov_b32 s96, 0
	s_barrier
	s_branch .LBB0_975

; #define PG8_STAGE(bufoff, gbase, voff) do { _Pragma("unroll") for (int _i = 0; _i < 2; ++_i) \
;         __builtin_amdgcn_global_load_lds((const unsigned*)((const char*)(gbase) + (voff)[_i]), (LAS unsigned*)(lds + (bufoff) + ldsw + _i * 8192), 16, 0, 0); } while (0)
; #define PG8_LDA(dst, b, h) do { _Pragma("unroll") for (int m = 0; m < 4; ++m) _Pragma("unroll") for (int k = 0; k < 2; ++k) dst[m][k] = *(const LAS bf16x8*)(lds + PG8_SA(b, h) + aoff + m * 2048 + k * 1024); } while (0)
; #define PG8_LDB(dst, b, h) do { _Pragma("unroll") for (int n = 0; n < 2; ++n) _Pragma("unroll") for (int k = 0; k < 2; ++k) dst[n][k] = *(const LAS bf16x8*)(lds + PG8_SB(b, h) + boff + n * 2048 + k * 1024); } while (0)
; #define PG8_MMA(ai, bj, At, Bt) do { __builtin_amdgcn_s_setprio(1); _Pragma("unroll") for (int m = 0; m < 4; ++m) _Pragma("unroll") for (int n = 0; n < 2; ++n) _Pragma("unroll") for (int k = 0; k < 2; ++k) \
;         acc[ai][bj][m][n] = __builtin_amdgcn_mfma_f32_16x16x32_bf16(Bt[n][k], At[m][k], acc[ai][bj][m][n], 0, 0, 0); __builtin_amdgcn_s_setprio(0); } while (0)
; #define PG8_WAIT_V(n) asm volatile("s_waitcnt vmcnt(" #n ")" ::: "memory")
; #define PG8_WAIT_L(n) asm volatile("s_waitcnt lgkmcnt(" #n ")" ::: "memory")
; #define PG8_BAR __builtin_amdgcn_s_barrier()
; #define PG8_SCHED __builtin_amdgcn_sched_barrier(0)
; template <class Epi, class Sched, bool ALIGN_EPI, bool SP2>
; __device__ __forceinline__ void gemm_phase(LAS unsigned char* lds, const Gemm g, const Sched& S, const Epi& E) {
;     ...
;             PG8_LDB(B0, 0, 0); PG8_LDB(B1, 0, 1); PG8_SCHED; PG8_LDA(At, 0, 0); PG8_STAGE(PG8_SA(1, 1), a1 + hstep, voffA);
;             PG8_WAIT_V(8); PG8_WAIT_L(0); PG8_BAR; PG8_MMA(0, 0, At, B0); PG8_MMA(0, 1, At, B1); PG8_BAR; PG8_SCHED;
;             PG8_LDA(At, 0, 1); PG8_STAGE(PG8_SB(0, 0), b2, voffB); PG8_STAGE(PG8_SB(0, 1), b2 + hstepB, voffB); PG8_STAGE(PG8_SA(0, 0), a2, voffA);
;             PG8_WAIT_V(8); PG8_WAIT_L(0); PG8_BAR; PG8_MMA(1, 0, At, B0); PG8_MMA(1, 1, At, B1); PG8_BAR; PG8_SCHED;
.LBB0_979:
	v_add_u32_e32 v131, s89, v210
	ds_read_b128 v[152:155], v131
	ds_read_b128 v[156:159], v131 offset:1024
	ds_read_b128 v[160:163], v131 offset:2048
	ds_read_b128 v[164:167], v131 offset:3072
	v_add_u32_e32 v131, s90, v210
	ds_read_b128 v[168:171], v131
	ds_read_b128 v[172:175], v131 offset:1024
	ds_read_b128 v[176:179], v131 offset:2048
	ds_read_b128 v[180:183], v131 offset:3072
	s_add_u32 s0, s76, 0xfff80080
	s_addc_u32 s58, s77, -1
	s_and_b64 s[14:15], s[78:79], exec
	s_cselect_b32 s81, s48, s58
	s_cselect_b32 s80, s49, s0
	s_cselect_b32 s79, s63, s97
	s_cselect_b32 s78, s65, s71
	v_lshl_add_u64 v[204:205], s[76:77], 0, v[142:143]
	s_add_i32 m0, s59, 0xc000
	ds_read_b128 v[184:187], v214
	ds_read_b128 v[188:191], v214 offset:1024
	ds_read_b128 v[192:195], v214 offset:2048
	ds_read_b128 v[196:199], v214 offset:3072
	ds_read_b128 v[200:203], v214 offset:4096
	ds_read_b128 v[216:219], v214 offset:5120
	ds_read_b128 v[220:223], v214 offset:6144
	ds_read_b128 v[224:227], v214 offset:7168
	global_load_lds_dwordx4 v[204:205], off
	v_lshl_add_u64 v[204:205], s[76:77], 0, v[144:145]
	s_add_i32 m0, s59, 0xc400
	s_nop 0
	global_load_lds_dwordx4 v[204:205], off
	s_waitcnt vmcnt(8)
	s_waitcnt lgkmcnt(0)
	s_barrier
	s_setprio 1
	v_mfma_f32_16x16x32_bf16 v[124:127], v[152:155], v[184:187], v[124:127]
	v_mfma_f32_16x16x32_bf16 v[120:123], v[160:163], v[184:187], v[120:123]
	v_mfma_f32_16x16x32_bf16 v[76:79], v[152:155], v[192:195], v[76:79]
	v_mfma_f32_16x16x32_bf16 v[28:31], v[160:163], v[192:195], v[28:31]
	v_mfma_f32_16x16x32_bf16 v[52:55], v[152:155], v[200:203], v[52:55]
	v_mfma_f32_16x16x32_bf16 v[20:23], v[160:163], v[200:203], v[20:23]
	v_mfma_f32_16x16x32_bf16 v[108:111], v[152:155], v[220:223], v[108:111]
	v_mfma_f32_16x16x32_bf16 v[104:107], v[160:163], v[220:223], v[104:107]
	v_mfma_f32_16x16x32_bf16 v[124:127], v[156:159], v[188:191], v[124:127]
	v_mfma_f32_16x16x32_bf16 v[120:123], v[164:167], v[188:191], v[120:123]
	v_mfma_f32_16x16x32_bf16 v[76:79], v[156:159], v[196:199], v[76:79]
	v_mfma_f32_16x16x32_bf16 v[28:31], v[164:167], v[196:199], v[28:31]
	v_mfma_f32_16x16x32_bf16 v[52:55], v[156:159], v[216:219], v[52:55]
	v_mfma_f32_16x16x32_bf16 v[20:23], v[164:167], v[216:219], v[20:23]
	v_mfma_f32_16x16x32_bf16 v[108:111], v[156:159], v[224:227], v[108:111]
	v_mfma_f32_16x16x32_bf16 v[104:107], v[164:167], v[224:227], v[104:107]
	v_mfma_f32_16x16x32_bf16 v[116:119], v[168:171], v[184:187], v[116:119]
	v_mfma_f32_16x16x32_bf16 v[112:115], v[176:179], v[184:187], v[112:115]
	v_mfma_f32_16x16x32_bf16 v[64:67], v[168:171], v[192:195], v[64:67]
	v_mfma_f32_16x16x32_bf16 v[24:27], v[176:179], v[192:195], v[24:27]
	v_mfma_f32_16x16x32_bf16 v[48:51], v[168:171], v[200:203], v[48:51]
	v_mfma_f32_16x16x32_bf16 v[16:19], v[176:179], v[200:203], v[16:19]
	v_mfma_f32_16x16x32_bf16 v[100:103], v[168:171], v[220:223], v[100:103]
	v_mfma_f32_16x16x32_bf16 v[96:99], v[176:179], v[220:223], v[96:99]
	v_mfma_f32_16x16x32_bf16 v[116:119], v[172:175], v[188:191], v[116:119]
	v_mfma_f32_16x16x32_bf16 v[112:115], v[180:183], v[188:191], v[112:115]
	v_mfma_f32_16x16x32_bf16 v[64:67], v[172:175], v[196:199], v[64:67]
	v_mfma_f32_16x16x32_bf16 v[24:27], v[180:183], v[196:199], v[24:27]
	v_mfma_f32_16x16x32_bf16 v[48:51], v[172:175], v[216:219], v[48:51]
	v_mfma_f32_16x16x32_bf16 v[16:19], v[180:183], v[216:219], v[16:19]
	v_mfma_f32_16x16x32_bf16 v[100:103], v[172:175], v[224:227], v[100:103]
	v_mfma_f32_16x16x32_bf16 v[96:99], v[180:183], v[224:227], v[96:99]
	s_setprio 0
	s_barrier
	s_add_i32 s0, s89, s57
	v_lshl_add_u64 v[204:205], s[78:79], 0, v[134:135]
	s_mov_b32 m0, s0
	ds_read_b128 v[184:187], v214 offset:16384
	ds_read_b128 v[188:191], v214 offset:17408
	ds_read_b128 v[192:195], v214 offset:18432
	ds_read_b128 v[196:199], v214 offset:19456
	ds_read_b128 v[200:203], v214 offset:20480
	ds_read_b128 v[216:219], v214 offset:21504
	ds_read_b128 v[220:223], v214 offset:22528
	ds_read_b128 v[224:227], v214 offset:23552
	global_load_lds_dwordx4 v[204:205], off
	s_add_i32 m0, s0, 0x400
	s_add_u32 s14, s78, 0x80000
	v_lshl_add_u64 v[228:229], s[78:79], 0, v[138:139]
	s_addc_u32 s15, s79, 0
	s_add_i32 s0, s90, s57
	global_load_lds_dwordx4 v[228:229], off
	v_lshl_add_u64 v[230:231], s[14:15], 0, v[134:135]
	s_mov_b32 m0, s0
	v_lshl_add_u64 v[232:233], s[80:81], 0, v[136:137]
	global_load_lds_dwordx4 v[230:231], off
	v_lshl_add_u64 v[230:231], s[14:15], 0, v[138:139]
	s_add_i32 m0, s0, 0x400
	s_nop 0
	global_load_lds_dwordx4 v[230:231], off
	v_lshl_add_u64 v[230:231], s[80:81], 0, v[132:133]
	s_mov_b32 m0, s59
	s_nop 0
	global_load_lds_dwordx4 v[230:231], off
	s_mov_b32 m0, s73
	s_nop 0
	global_load_lds_dwordx4 v[232:233], off
	s_waitcnt vmcnt(8)
	s_waitcnt lgkmcnt(0)
	s_barrier
; #define PG8_STAGE(bufoff, gbase, voff) do { _Pragma("unroll") for (int _i = 0; _i < 2; ++_i) \
;         __builtin_amdgcn_global_load_lds((const unsigned*)((const char*)(gbase) + (voff)[_i]), (LAS unsigned*)(lds + (bufoff) + ldsw + _i * 8192), 16, 0, 0); } while (0)
; #define PG8_LDA(dst, b, h) do { _Pragma("unroll") for (int m = 0; m < 4; ++m) _Pragma("unroll") for (int k = 0; k < 2; ++k) dst[m][k] = *(const LAS bf16x8*)(lds + PG8_SA(b, h) + aoff + m * 2048 + k * 1024); } while (0)
; #define PG8_LDB(dst, b, h) do { _Pragma("unroll") for (int n = 0; n < 2; ++n) _Pragma("unroll") for (int k = 0; k < 2; ++k) dst[n][k] = *(const LAS bf16x8*)(lds + PG8_SB(b, h) + boff + n * 2048 + k * 1024); } while (0)
; #define PG8_MMA(ai, bj, At, Bt) do { __builtin_amdgcn_s_setprio(1); _Pragma("unroll") for (int m = 0; m < 4; ++m) _Pragma("unroll") for (int n = 0; n < 2; ++n) _Pragma("unroll") for (int k = 0; k < 2; ++k) \
;         acc[ai][bj][m][n] = __builtin_amdgcn_mfma_f32_16x16x32_bf16(Bt[n][k], At[m][k], acc[ai][bj][m][n], 0, 0, 0); __builtin_amdgcn_s_setprio(0); } while (0)
; #define PG8_WAIT_V(n) asm volatile("s_waitcnt vmcnt(" #n ")" ::: "memory")
; #define PG8_WAIT_L(n) asm volatile("s_waitcnt lgkmcnt(" #n ")" ::: "memory")
; #define PG8_BAR __builtin_amdgcn_s_barrier()
; #define PG8_SCHED __builtin_amdgcn_sched_barrier(0)
; template <class Epi, class Sched, bool ALIGN_EPI, bool SP2>
; __device__ __forceinline__ void gemm_phase(LAS unsigned char* lds, const Gemm g, const Sched& S, const Epi& E) {
;     ...
;             PG8_WAIT_V(8); PG8_WAIT_L(0); PG8_BAR; PG8_MMA(1, 0, At, B0); PG8_MMA(1, 1, At, B1); PG8_BAR; PG8_SCHED;
;             PG8_LDB(B0, 1, 0); PG8_LDB(B1, 1, 1); PG8_SCHED; PG8_LDA(At, 1, 0); PG8_STAGE(PG8_SA(0, 1), a2 + hstep, voffA);
;             PG8_WAIT_V(8); PG8_WAIT_L(0); PG8_BAR; PG8_MMA(0, 0, At, B0); PG8_MMA(0, 1, At, B1); PG8_BAR; PG8_SCHED;
	s_setprio 1
	v_mfma_f32_16x16x32_bf16 v[92:95], v[152:155], v[184:187], v[92:95]
	v_mfma_f32_16x16x32_bf16 v[88:91], v[160:163], v[184:187], v[88:91]
	v_mfma_f32_16x16x32_bf16 v[44:47], v[152:155], v[192:195], v[44:47]
	v_mfma_f32_16x16x32_bf16 v[12:15], v[160:163], v[192:195], v[12:15]
	v_mfma_f32_16x16x32_bf16 v[36:39], v[152:155], v[200:203], v[36:39]
	v_mfma_f32_16x16x32_bf16 v[4:7], v[160:163], v[200:203], v[4:7]
	v_mfma_f32_16x16x32_bf16 v[72:75], v[152:155], v[220:223], v[72:75]
	v_mfma_f32_16x16x32_bf16 v[68:71], v[160:163], v[220:223], v[68:71]
	v_mfma_f32_16x16x32_bf16 v[92:95], v[156:159], v[188:191], v[92:95]
	v_mfma_f32_16x16x32_bf16 v[88:91], v[164:167], v[188:191], v[88:91]
	v_mfma_f32_16x16x32_bf16 v[44:47], v[156:159], v[196:199], v[44:47]
	v_mfma_f32_16x16x32_bf16 v[12:15], v[164:167], v[196:199], v[12:15]
	v_mfma_f32_16x16x32_bf16 v[36:39], v[156:159], v[216:219], v[36:39]
	v_mfma_f32_16x16x32_bf16 v[4:7], v[164:167], v[216:219], v[4:7]
	v_mfma_f32_16x16x32_bf16 v[72:75], v[156:159], v[224:227], v[72:75]
	v_mfma_f32_16x16x32_bf16 v[68:71], v[164:167], v[224:227], v[68:71]
	v_mfma_f32_16x16x32_bf16 v[84:87], v[168:171], v[184:187], v[84:87]
	v_mfma_f32_16x16x32_bf16 v[80:83], v[176:179], v[184:187], v[80:83]
	v_mfma_f32_16x16x32_bf16 v[40:43], v[168:171], v[192:195], v[40:43]
	v_mfma_f32_16x16x32_bf16 v[8:11], v[176:179], v[192:195], v[8:11]
	v_mfma_f32_16x16x32_bf16 v[32:35], v[168:171], v[200:203], v[32:35]
	v_mfma_f32_16x16x32_bf16 v[0:3], v[176:179], v[200:203], v[0:3]
	v_mfma_f32_16x16x32_bf16 v[60:63], v[168:171], v[220:223], v[60:63]
	v_mfma_f32_16x16x32_bf16 v[56:59], v[176:179], v[220:223], v[56:59]
	v_mfma_f32_16x16x32_bf16 v[84:87], v[172:175], v[188:191], v[84:87]
	v_mfma_f32_16x16x32_bf16 v[80:83], v[180:183], v[188:191], v[80:83]
	v_mfma_f32_16x16x32_bf16 v[40:43], v[172:175], v[196:199], v[40:43]
	v_mfma_f32_16x16x32_bf16 v[8:11], v[180:183], v[196:199], v[8:11]
	v_mfma_f32_16x16x32_bf16 v[32:35], v[172:175], v[216:219], v[32:35]
	v_mfma_f32_16x16x32_bf16 v[0:3], v[180:183], v[216:219], v[0:3]
	v_mfma_f32_16x16x32_bf16 v[60:63], v[172:175], v[224:227], v[60:63]
	v_mfma_f32_16x16x32_bf16 v[56:59], v[180:183], v[224:227], v[56:59]
	s_setprio 0
	s_barrier
	s_add_i32 s0, 0, 0x18000
	v_add_u32_e32 v131, s0, v210
	s_add_i32 s58, 0, 0x1c000
	ds_read_b128 v[152:155], v131
	ds_read_b128 v[156:159], v131 offset:1024
	ds_read_b128 v[160:163], v131 offset:2048
	ds_read_b128 v[164:167], v131 offset:3072
	v_add_u32_e32 v131, s58, v210
	ds_read_b128 v[168:171], v131
	ds_read_b128 v[172:175], v131 offset:1024
	ds_read_b128 v[176:179], v131 offset:2048
	ds_read_b128 v[180:183], v131 offset:3072
	s_add_u32 s14, s80, 0x80000
	s_addc_u32 s15, s81, 0
	s_mov_b32 m0, s84
	v_lshl_add_u64 v[234:235], s[14:15], 0, v[132:133]
	ds_read_b128 v[184:187], v214 offset:32768
	ds_read_b128 v[188:191], v214 offset:33792
	ds_read_b128 v[192:195], v214 offset:34816
	ds_read_b128 v[196:199], v214 offset:35840
	ds_read_b128 v[200:203], v214 offset:36864
	ds_read_b128 v[216:219], v214 offset:37888
	ds_read_b128 v[220:223], v214 offset:38912
	ds_read_b128 v[224:227], v214 offset:39936
	global_load_lds_dwordx4 v[234:235], off
	v_lshl_add_u64 v[234:235], s[14:15], 0, v[136:137]
	s_mov_b32 m0, s85
	s_nop 0
	global_load_lds_dwordx4 v[234:235], off
	s_waitcnt vmcnt(8)
	s_waitcnt lgkmcnt(0)
	s_barrier
	s_setprio 1
	v_mfma_f32_16x16x32_bf16 v[124:127], v[152:155], v[184:187], v[124:127]
	v_mfma_f32_16x16x32_bf16 v[120:123], v[160:163], v[184:187], v[120:123]
	v_mfma_f32_16x16x32_bf16 v[76:79], v[152:155], v[192:195], v[76:79]
	v_mfma_f32_16x16x32_bf16 v[28:31], v[160:163], v[192:195], v[28:31]
	v_mfma_f32_16x16x32_bf16 v[52:55], v[152:155], v[200:203], v[52:55]
	v_mfma_f32_16x16x32_bf16 v[20:23], v[160:163], v[200:203], v[20:23]
	v_mfma_f32_16x16x32_bf16 v[108:111], v[152:155], v[220:223], v[108:111]
	v_mfma_f32_16x16x32_bf16 v[104:107], v[160:163], v[220:223], v[104:107]
	v_mfma_f32_16x16x32_bf16 v[124:127], v[156:159], v[188:191], v[124:127]
	v_mfma_f32_16x16x32_bf16 v[120:123], v[164:167], v[188:191], v[120:123]
	v_mfma_f32_16x16x32_bf16 v[76:79], v[156:159], v[196:199], v[76:79]
	v_mfma_f32_16x16x32_bf16 v[28:31], v[164:167], v[196:199], v[28:31]
	v_mfma_f32_16x16x32_bf16 v[52:55], v[156:159], v[216:219], v[52:55]
	v_mfma_f32_16x16x32_bf16 v[20:23], v[164:167], v[216:219], v[20:23]
	v_mfma_f32_16x16x32_bf16 v[108:111], v[156:159], v[224:227], v[108:111]
	v_mfma_f32_16x16x32_bf16 v[104:107], v[164:167], v[224:227], v[104:107]
	v_mfma_f32_16x16x32_bf16 v[116:119], v[168:171], v[184:187], v[116:119]
	v_mfma_f32_16x16x32_bf16 v[112:115], v[176:179], v[184:187], v[112:115]
	v_mfma_f32_16x16x32_bf16 v[64:67], v[168:171], v[192:195], v[64:67]
	v_mfma_f32_16x16x32_bf16 v[24:27], v[176:179], v[192:195], v[24:27]
	v_mfma_f32_16x16x32_bf16 v[48:51], v[168:171], v[200:203], v[48:51]
	v_mfma_f32_16x16x32_bf16 v[16:19], v[176:179], v[200:203], v[16:19]
	v_mfma_f32_16x16x32_bf16 v[100:103], v[168:171], v[220:223], v[100:103]
	v_mfma_f32_16x16x32_bf16 v[96:99], v[176:179], v[220:223], v[96:99]
	v_mfma_f32_16x16x32_bf16 v[116:119], v[172:175], v[188:191], v[116:119]
	v_mfma_f32_16x16x32_bf16 v[112:115], v[180:183], v[188:191], v[112:115]
	v_mfma_f32_16x16x32_bf16 v[64:67], v[172:175], v[196:199], v[64:67]
	v_mfma_f32_16x16x32_bf16 v[24:27], v[180:183], v[196:199], v[24:27]
	v_mfma_f32_16x16x32_bf16 v[48:51], v[172:175], v[216:219], v[48:51]
	v_mfma_f32_16x16x32_bf16 v[16:19], v[180:183], v[216:219], v[16:19]
	v_mfma_f32_16x16x32_bf16 v[100:103], v[172:175], v[224:227], v[100:103]
	v_mfma_f32_16x16x32_bf16 v[96:99], v[180:183], v[224:227], v[96:99]
	s_setprio 0
	s_barrier
; #define PG8_STAGE(bufoff, gbase, voff) do { _Pragma("unroll") for (int _i = 0; _i < 2; ++_i) \
;         __builtin_amdgcn_global_load_lds((const unsigned*)((const char*)(gbase) + (voff)[_i]), (LAS unsigned*)(lds + (bufoff) + ldsw + _i * 8192), 16, 0, 0); } while (0)
; #define PG8_LDA(dst, b, h) do { _Pragma("unroll") for (int m = 0; m < 4; ++m) _Pragma("unroll") for (int k = 0; k < 2; ++k) dst[m][k] = *(const LAS bf16x8*)(lds + PG8_SA(b, h) + aoff + m * 2048 + k * 1024); } while (0)
; #define PG8_MMA(ai, bj, At, Bt) do { __builtin_amdgcn_s_setprio(1); _Pragma("unroll") for (int m = 0; m < 4; ++m) _Pragma("unroll") for (int n = 0; n < 2; ++n) _Pragma("unroll") for (int k = 0; k < 2; ++k) \
;         acc[ai][bj][m][n] = __builtin_amdgcn_mfma_f32_16x16x32_bf16(Bt[n][k], At[m][k], acc[ai][bj][m][n], 0, 0, 0); __builtin_amdgcn_s_setprio(0); } while (0)
; #define PG8_WAIT_V(n) asm volatile("s_waitcnt vmcnt(" #n ")" ::: "memory")
; #define PG8_WAIT_L(n) asm volatile("s_waitcnt lgkmcnt(" #n ")" ::: "memory")
; #define PG8_BAR __builtin_amdgcn_s_barrier()
; #define PG8_SCHED __builtin_amdgcn_sched_barrier(0)
; template <class Epi, class Sched, bool ALIGN_EPI, bool SP2>
; __device__ __forceinline__ void gemm_phase(LAS unsigned char* lds, const Gemm g, const Sched& S, const Epi& E) {
;     ...
;         for (int t = tb; t < te; t += 2) {
;             const bool last = (t == nt - 2);
;     ...
;             PG8_LDA(At, 1, 1); PG8_STAGE(PG8_SB(1, 0), b3, voffB); PG8_STAGE(PG8_SB(1, 1), b3 + hstepB, voffB); PG8_STAGE(PG8_SA(1, 0), a3, voffA);
;             PG8_WAIT_V(8); PG8_WAIT_L(0); PG8_BAR; PG8_MMA(1, 0, At, B0); PG8_MMA(1, 1, At, B1); PG8_BAR; PG8_SCHED;
	s_add_i32 s0, s0, s57
	v_lshl_add_u64 v[204:205], v[204:205], 0, s[42:43]
	s_mov_b32 m0, s0
	ds_read_b128 v[184:187], v214 offset:49152
	ds_read_b128 v[188:191], v214 offset:50176
	ds_read_b128 v[192:195], v214 offset:51200
	ds_read_b128 v[196:199], v214 offset:52224
	ds_read_b128 v[200:203], v214 offset:53248
	ds_read_b128 v[216:219], v214 offset:54272
	ds_read_b128 v[220:223], v214 offset:55296
	ds_read_b128 v[224:227], v214 offset:56320
	global_load_lds_dwordx4 v[204:205], off
	s_add_i32 m0, s0, 0x400
	s_add_u32 s14, s78, 0x80080
	v_lshl_add_u64 v[204:205], v[228:229], 0, s[42:43]
	s_addc_u32 s15, s79, 0
	s_add_i32 s0, s58, s57
	global_load_lds_dwordx4 v[204:205], off
	v_lshl_add_u64 v[204:205], s[14:15], 0, v[134:135]
	s_mov_b32 m0, s0
	s_nop 0
	global_load_lds_dwordx4 v[204:205], off
	v_lshl_add_u64 v[204:205], s[14:15], 0, v[138:139]
	s_add_i32 m0, s0, 0x400
	s_nop 0
	global_load_lds_dwordx4 v[204:205], off
	v_lshl_add_u64 v[204:205], v[230:231], 0, s[42:43]
	s_mov_b32 m0, s87
	s_nop 0
	global_load_lds_dwordx4 v[204:205], off
	v_lshl_add_u64 v[204:205], v[232:233], 0, s[42:43]
	s_mov_b32 m0, s88
	s_nop 0
	global_load_lds_dwordx4 v[204:205], off
	s_waitcnt vmcnt(8)
	s_waitcnt lgkmcnt(0)
	s_barrier
	s_setprio 1
	v_mfma_f32_16x16x32_bf16 v[92:95], v[152:155], v[184:187], v[92:95]
	v_mfma_f32_16x16x32_bf16 v[88:91], v[160:163], v[184:187], v[88:91]
	v_mfma_f32_16x16x32_bf16 v[44:47], v[152:155], v[192:195], v[44:47]
	v_mfma_f32_16x16x32_bf16 v[12:15], v[160:163], v[192:195], v[12:15]
	v_mfma_f32_16x16x32_bf16 v[36:39], v[152:155], v[200:203], v[36:39]
	v_mfma_f32_16x16x32_bf16 v[4:7], v[160:163], v[200:203], v[4:7]
	v_mfma_f32_16x16x32_bf16 v[72:75], v[152:155], v[220:223], v[72:75]
	v_mfma_f32_16x16x32_bf16 v[68:71], v[160:163], v[220:223], v[68:71]
	v_mfma_f32_16x16x32_bf16 v[92:95], v[156:159], v[188:191], v[92:95]
	v_mfma_f32_16x16x32_bf16 v[88:91], v[164:167], v[188:191], v[88:91]
	v_mfma_f32_16x16x32_bf16 v[44:47], v[156:159], v[196:199], v[44:47]
	v_mfma_f32_16x16x32_bf16 v[12:15], v[164:167], v[196:199], v[12:15]
	v_mfma_f32_16x16x32_bf16 v[36:39], v[156:159], v[216:219], v[36:39]
	v_mfma_f32_16x16x32_bf16 v[4:7], v[164:167], v[216:219], v[4:7]
	v_mfma_f32_16x16x32_bf16 v[72:75], v[156:159], v[224:227], v[72:75]
	v_mfma_f32_16x16x32_bf16 v[68:71], v[164:167], v[224:227], v[68:71]
	v_mfma_f32_16x16x32_bf16 v[84:87], v[168:171], v[184:187], v[84:87]
	v_mfma_f32_16x16x32_bf16 v[80:83], v[176:179], v[184:187], v[80:83]
	v_mfma_f32_16x16x32_bf16 v[40:43], v[168:171], v[192:195], v[40:43]
	v_mfma_f32_16x16x32_bf16 v[8:11], v[176:179], v[192:195], v[8:11]
	v_mfma_f32_16x16x32_bf16 v[32:35], v[168:171], v[200:203], v[32:35]
	v_mfma_f32_16x16x32_bf16 v[0:3], v[176:179], v[200:203], v[0:3]
	v_mfma_f32_16x16x32_bf16 v[60:63], v[168:171], v[220:223], v[60:63]
	v_mfma_f32_16x16x32_bf16 v[56:59], v[176:179], v[220:223], v[56:59]
	v_mfma_f32_16x16x32_bf16 v[84:87], v[172:175], v[188:191], v[84:87]
	v_mfma_f32_16x16x32_bf16 v[80:83], v[180:183], v[188:191], v[80:83]
	v_mfma_f32_16x16x32_bf16 v[40:43], v[172:175], v[196:199], v[40:43]
	v_mfma_f32_16x16x32_bf16 v[8:11], v[180:183], v[196:199], v[8:11]
	v_mfma_f32_16x16x32_bf16 v[32:35], v[172:175], v[216:219], v[32:35]
	v_mfma_f32_16x16x32_bf16 v[0:3], v[180:183], v[216:219], v[0:3]
	v_mfma_f32_16x16x32_bf16 v[60:63], v[172:175], v[224:227], v[60:63]
	v_mfma_f32_16x16x32_bf16 v[56:59], v[180:183], v[224:227], v[56:59]
	s_setprio 0
	s_barrier
	s_add_i32 s33, s33, 2
	s_add_u32 s76, s76, 0x100
	s_addc_u32 s77, s77, 0
	s_add_u32 s71, s71, 0x100
	s_addc_u32 s97, s97, 0
	s_cmp_gt_u32 s33, 29
	s_cbranch_scc1 .LBB0_987
